# attention combine: hoist the four in-place gate loads to the start of the combine (private round-1 tail copy)
# baseline (speedup 1.0000x reference)
; DI void attn_block(const Params& p, int isP, int sq, int c, int h) {
;     ...
;   float* OS = (float*)smem;
;   float* LS = OS + 4 * 2048;
;   bfr* gay = (bfr*)(p.ws + W_GA);
; #pragma unroll
;   for (int rd = 0; rd < 2; ++rd) {
;     __syncthreads();
; #pragma unroll
;     for (int q2 = 0; q2 < 2; ++q2) {
;       const int qt = rd * 2 + q2;
;       float l = lsum[qt];
;       l += __shfl_xor(l, 16);
;       l += __shfl_xor(l, 32);
;       LS[(wid * 2 + q2) * 64 + lane] = l;
; #pragma unroll
;       for (int dt = 0; dt < 4; ++dt)
; #pragma unroll
;         for (int j = 0; j < 4; ++j) OS[((wid * 2 + q2) * 16 + dt * 4 + j) * 64 + lane] = o[qt][dt][j];
;     }
;     __syncthreads();
;     const int q2 = wid >> 1, qt = rd * 2 + q2;
;     if (qt < nqt) {
;       float l = 0.f;
; #pragma unroll
;       for (int w = 0; w < 4; ++w) l += LS[(w * 2 + q2) * 64 + lane];
;       const float inv = l > 0.f ? 1.f / l : 0.f;
;       const long rowoff = (long)(qrow0 + qt * 16 + fr) * 512 + h * 64;
; #pragma unroll
;       for (int d2 = 0; d2 < 2; ++d2) {
;         const int dt = (wid & 1) * 2 + d2;
;         float acc4[4];
; #pragma unroll
;         for (int j = 0; j < 4; ++j) {
;           float a = 0.f;
; #pragma unroll
;           for (int w = 0; w < 4; ++w) a += OS[((w * 2 + q2) * 16 + dt * 4 + j) * 64 + lane];
;           acc4[j] = a * inv;
;         }
;         uint2* ptr = (uint2*)(gay + rowoff + dt * 16 + fq * 4);
;         uint2 gv = *ptr;
;         float g0 = __uint_as_float(gv.x << 16), g1 = __uint_as_float(gv.x & 0xFFFF0000u);
;         float g2 = __uint_as_float(gv.y << 16), g3 = __uint_as_float(gv.y & 0xFFFF0000u);
;         uint2 ov;
;         ov.x = pack2(acc4[0] * g0, acc4[1] * g1);
;         ov.y = pack2(acc4[2] * g2, acc4[3] * g3);
;         *ptr = ov;
;       }
;     }
.LBB0_4862:
	v_and_b32_e32 v16, 63, v141
	v_lshl_add_u32 v50, v16, 2, v169
	ds_bpermute_b32 v16, v180, v146
	s_lshl_b32 s9, s6, 1
	s_ashr_i32 s8, s19, 7
	s_add_u32 s0, s14, s20
	s_addc_u32 s1, s15, 0
	s_waitcnt lgkmcnt(0)
	v_add_f32_e32 v16, v146, v16
	ds_bpermute_b32 v17, v139, v16
	v_mov_b32_e32 v141, v129
	v_lshl_add_u64 v[48:49], s[0:1], 0, v[140:141]
	s_and_b32 s90, s9, 2
	s_lshl_b32 s90, s90, 5
	v_lshl_add_u32 v194, s8, 4, v138
	v_lshl_add_u32 v198, s8, 4, v136
	v_ashrrev_i32_e32 v195, 31, v194
	v_ashrrev_i32_e32 v199, 31, v198
	v_lshlrev_b64 v[194:195], 10, v[194:195]
	v_lshlrev_b64 v[198:199], 10, v[198:199]
	v_lshl_add_u64 v[194:195], v[48:49], 0, v[194:195]
	v_lshl_add_u64 v[198:199], v[48:49], 0, v[198:199]
	v_lshl_add_u64 v[194:195], v[194:195], 0, s[90:91]
	v_lshl_add_u64 v[198:199], v[198:199], 0, s[90:91]
	global_load_dwordx2 v[186:187], v[194:195], off
	global_load_dwordx2 v[188:189], v[194:195], off offset:32
	global_load_dwordx2 v[190:191], v[198:199], off
	global_load_dwordx2 v[192:193], v[198:199], off offset:32
	s_lshl_b32 s0, s6, 9
	v_add_u32_e32 v46, s0, v50
	s_waitcnt lgkmcnt(0)
	v_add_f32_e32 v16, v16, v17
	s_barrier
	ds_write_b32 v46, v16 offset:32768
	ds_bpermute_b32 v16, v180, v147
	s_lshl_b32 s0, s6, 13
	v_add_u32_e32 v17, s0, v50
	s_or_b32 s0, s9, 1
	s_lshl_b32 s18, s8, 8
	s_waitcnt lgkmcnt(0)
	v_add_f32_e32 v16, v147, v16
	ds_bpermute_b32 v18, v139, v16
	s_and_b32 s7, s9, 2
	s_lshl_b32 s1, s0, 8
	s_lshl_b32 s0, s0, 12
	v_add_u32_e32 v52, s1, v50
	s_waitcnt lgkmcnt(0)
	v_add_f32_e32 v16, v16, v18
	v_add_u32_e32 v51, s0, v50
	s_cmp_gt_i32 s8, 3
	v_add_u32_e32 v47, s18, v50
	ds_write2st64_b32 v17, v64, v65 offset1:1
	ds_write2st64_b32 v17, v66, v67 offset0:2 offset1:3
	ds_write2st64_b32 v17, v92, v93 offset0:4 offset1:5
	ds_write2st64_b32 v17, v94, v95 offset0:6 offset1:7
	ds_write2st64_b32 v17, v88, v89 offset0:8 offset1:9
	ds_write2st64_b32 v17, v90, v91 offset0:10 offset1:11
	ds_write2st64_b32 v17, v84, v85 offset0:12 offset1:13
	ds_write2st64_b32 v17, v86, v87 offset0:14 offset1:15
	ds_write_b32 v52, v16 offset:32768
	ds_write2st64_b32 v51, v80, v81 offset1:1
	ds_write2st64_b32 v51, v82, v83 offset0:2 offset1:3
	ds_write2st64_b32 v51, v76, v77 offset0:4 offset1:5
	ds_write2st64_b32 v51, v78, v79 offset0:6 offset1:7
	ds_write2st64_b32 v51, v72, v73 offset0:8 offset1:9
	ds_write2st64_b32 v51, v74, v75 offset0:10 offset1:11
	ds_write2st64_b32 v51, v68, v69 offset0:12 offset1:13
	ds_write2st64_b32 v51, v70, v71 offset0:14 offset1:15
	s_waitcnt lgkmcnt(0)
	s_barrier
	s_cbranch_scc1 .LBB0_4864
	ds_read2st64_b32 v[18:19], v47 offset0:128 offset1:130
	s_lshl_b32 s90, s7, 5
	s_waitcnt lgkmcnt(0)
	v_add_f32_e32 v16, 0, v18
	v_add_f32_e32 v16, v16, v19
	ds_read2st64_b32 v[18:19], v47 offset0:132 offset1:134
	s_waitcnt lgkmcnt(0)
	v_add_f32_e32 v16, v16, v18
	v_add_f32_e32 v16, v16, v19
	v_div_scale_f32 v18, s[18:19], v16, v16, 1.0
	v_rcp_f32_e32 v19, v18
	v_cmp_lt_f32_e64 s[0:1], 0, v16
	v_fma_f32 v24, -v18, v19, 1.0
	v_fmac_f32_e32 v19, v24, v19
	v_div_scale_f32 v24, vcc, 1.0, v16, 1.0
	v_mul_f32_e32 v25, v24, v19
	v_fma_f32 v26, -v18, v25, v24
	v_fmac_f32_e32 v25, v26, v19
	v_fma_f32 v18, -v18, v25, v24
	v_div_fmas_f32 v18, v18, v19, v25
	v_div_fixup_f32 v16, v18, v16, 1.0
	v_lshl_add_u32 v18, s8, 4, v138
	v_ashrrev_i32_e32 v19, 31, v18
	v_cndmask_b32_e64 v16, 0, v16, s[0:1]
	v_lshlrev_b64 v[18:19], 10, v[18:19]
	s_lshl_b32 s1, s7, 10
	s_lshl_b32 s0, s8, 12
	v_lshl_add_u64 v[24:25], v[48:49], 0, v[18:19]
	s_or_b32 s1, s1, s0
	v_add_u32_e32 v53, s1, v50
	v_lshl_add_u64 v[60:61], v[24:25], 0, s[90:91]
	ds_read2st64_b32 v[18:19], v53 offset1:1
	ds_read2st64_b32 v[26:27], v53 offset0:32 offset1:33
	ds_read2st64_b32 v[36:37], v53 offset0:64 offset1:65
	ds_read2st64_b32 v[38:39], v53 offset0:96 offset1:97
	ds_read2st64_b32 v[44:45], v53 offset0:2 offset1:3
	ds_read2st64_b32 v[54:55], v53 offset0:34 offset1:35
	ds_read2st64_b32 v[56:57], v53 offset0:66 offset1:67
	ds_read2st64_b32 v[58:59], v53 offset0:98 offset1:99
	s_waitcnt lgkmcnt(7)
	v_pk_add_f32 v[18:19], v[18:19], 0 op_sel_hi:[1,0]
	s_or_b32 s1, s7, 1
	s_waitcnt lgkmcnt(6)
	v_pk_add_f32 v[18:19], v[18:19], v[26:27]
	s_waitcnt lgkmcnt(3)
	v_pk_add_f32 v[26:27], v[44:45], 0 op_sel_hi:[1,0]
	v_pk_add_f32 v[18:19], v[18:19], v[36:37]
	s_waitcnt lgkmcnt(2)
	v_pk_add_f32 v[26:27], v[26:27], v[54:55]
	v_pk_add_f32 v[18:19], v[18:19], v[38:39]
	s_waitcnt lgkmcnt(1)
	v_pk_add_f32 v[26:27], v[26:27], v[56:57]
	v_pk_mul_f32 v[18:19], v[16:17], v[18:19] op_sel_hi:[0,1]
	s_waitcnt lgkmcnt(0)
	v_pk_add_f32 v[26:27], v[26:27], v[58:59]
	s_lshl_b32 s6, s1, 10
	v_pk_mul_f32 v[26:27], v[16:17], v[26:27] op_sel_hi:[0,1]
	s_or_b32 s0, s6, s0
	s_lshl_b32 s90, s1, 5
	v_lshl_add_u64 v[24:25], v[24:25], 0, s[90:91]
	s_waitcnt vmcnt(0)
	v_lshlrev_b32_e32 v64, 16, v186
	v_and_b32_e32 v65, 0xffff0000, v186
	v_lshlrev_b32_e32 v62, 16, v187
	v_and_b32_e32 v63, 0xffff0000, v187
	v_pk_mul_f32 v[18:19], v[18:19], v[64:65]
	v_pk_mul_f32 v[26:27], v[26:27], v[62:63]
	v_cvt_pk_bf16_f32 v18, v18, v19
	v_cvt_pk_bf16_f32 v19, v26, v27
	global_store_dwordx2 v[60:61], v[18:19], off
	v_add_u32_e32 v18, s0, v50
	ds_read2st64_b32 v[54:55], v18 offset1:1
	ds_read2st64_b32 v[56:57], v18 offset0:32 offset1:33
	ds_read2st64_b32 v[58:59], v18 offset0:64 offset1:65
	ds_read2st64_b32 v[60:61], v18 offset0:96 offset1:97
	ds_read2st64_b32 v[44:45], v18 offset0:2 offset1:3
	ds_read2st64_b32 v[38:39], v18 offset0:34 offset1:35
	ds_read2st64_b32 v[36:37], v18 offset0:66 offset1:67
	ds_read2st64_b32 v[18:19], v18 offset0:98 offset1:99
	s_waitcnt lgkmcnt(7)
	v_pk_add_f32 v[54:55], v[54:55], 0 op_sel_hi:[1,0]
	s_waitcnt lgkmcnt(3)
	v_pk_add_f32 v[44:45], v[44:45], 0 op_sel_hi:[1,0]
	v_pk_add_f32 v[54:55], v[54:55], v[56:57]
	s_waitcnt lgkmcnt(2)
	v_pk_add_f32 v[38:39], v[44:45], v[38:39]
	v_pk_add_f32 v[54:55], v[54:55], v[58:59]
	s_waitcnt lgkmcnt(1)
	v_pk_add_f32 v[36:37], v[38:39], v[36:37]
	v_pk_add_f32 v[54:55], v[54:55], v[60:61]
	s_waitcnt lgkmcnt(0)
	v_pk_add_f32 v[18:19], v[36:37], v[18:19]
	v_pk_mul_f32 v[54:55], v[16:17], v[54:55] op_sel_hi:[0,1]
	v_pk_mul_f32 v[18:19], v[16:17], v[18:19] op_sel_hi:[0,1]
	v_lshlrev_b32_e32 v62, 16, v188
	v_and_b32_e32 v63, 0xffff0000, v188
	v_lshlrev_b32_e32 v26, 16, v189
	v_and_b32_e32 v27, 0xffff0000, v189
	v_pk_mul_f32 v[54:55], v[54:55], v[62:63]
	v_pk_mul_f32 v[18:19], v[18:19], v[26:27]
	v_cvt_pk_bf16_f32 v54, v54, v55
	v_cvt_pk_bf16_f32 v55, v18, v19
	global_store_dwordx2 v[24:25], v[54:55], off

; DI void attn_block(const Params& p, int isP, int sq, int c, int h) {
;     ...
;     const int q2 = wid >> 1, qt = rd * 2 + q2;
;     if (qt < nqt) {
;       float l = 0.f;
; #pragma unroll
;       for (int w = 0; w < 4; ++w) l += LS[(w * 2 + q2) * 64 + lane];
;       const float inv = l > 0.f ? 1.f / l : 0.f;
;       const long rowoff = (long)(qrow0 + qt * 16 + fr) * 512 + h * 64;
; #pragma unroll
;       for (int d2 = 0; d2 < 2; ++d2) {
;         const int dt = (wid & 1) * 2 + d2;
;         float acc4[4];
; #pragma unroll
;         for (int j = 0; j < 4; ++j) {
;           float a = 0.f;
; #pragma unroll
;           for (int w = 0; w < 4; ++w) a += OS[((w * 2 + q2) * 16 + dt * 4 + j) * 64 + lane];
;           acc4[j] = a * inv;
;         }
;         uint2* ptr = (uint2*)(gay + rowoff + dt * 16 + fq * 4);
;         uint2 gv = *ptr;
;         float g0 = __uint_as_float(gv.x << 16), g1 = __uint_as_float(gv.x & 0xFFFF0000u);
;         float g2 = __uint_as_float(gv.y << 16), g3 = __uint_as_float(gv.y & 0xFFFF0000u);
;         uint2 ov;
;         ov.x = pack2(acc4[0] * g0, acc4[1] * g1);
;         ov.y = pack2(acc4[2] * g2, acc4[3] * g3);
;         *ptr = ov;
;       }
;     }
.Latg_66:
	s_and_b64 vcc, exec, s[4:5]
	s_cbranch_vccz .Latg_skip
	v_ashrrev_i32_e32 v3, 31, v2
	v_lshlrev_b64 v[2:3], 10, v[2:3]
	s_lshl_b32 s1, s7, 10
	s_lshl_b32 s0, s8, 12
	v_lshl_add_u64 v[2:3], v[48:49], 0, v[2:3]
	s_or_b32 s1, s0, s1
	s_lshl_b32 s90, s7, 5
	v_add_u32_e32 v1, s1, v50
	v_lshl_add_u64 v[20:21], v[2:3], 0, s[90:91]
	ds_read2st64_b32 v[4:5], v1 offset1:1
	ds_read2st64_b32 v[6:7], v1 offset0:32 offset1:33
	ds_read2st64_b32 v[8:9], v1 offset0:64 offset1:65
	ds_read2st64_b32 v[10:11], v1 offset0:96 offset1:97
	ds_read2st64_b32 v[12:13], v1 offset0:2 offset1:3
	ds_read2st64_b32 v[14:15], v1 offset0:34 offset1:35
	ds_read2st64_b32 v[16:17], v1 offset0:66 offset1:67
	ds_read2st64_b32 v[18:19], v1 offset0:98 offset1:99
	s_waitcnt lgkmcnt(7)
	v_pk_add_f32 v[4:5], v[4:5], 0 op_sel_hi:[1,0]
	s_or_b32 s1, s7, 1
	s_waitcnt lgkmcnt(6)
	v_pk_add_f32 v[4:5], v[4:5], v[6:7]
	s_waitcnt lgkmcnt(3)
	v_pk_add_f32 v[6:7], v[12:13], 0 op_sel_hi:[1,0]
	v_pk_add_f32 v[4:5], v[4:5], v[8:9]
	s_waitcnt lgkmcnt(2)
	v_pk_add_f32 v[6:7], v[6:7], v[14:15]
	v_pk_add_f32 v[4:5], v[4:5], v[10:11]
	s_waitcnt lgkmcnt(1)
	v_pk_add_f32 v[6:7], v[6:7], v[16:17]
	v_pk_mul_f32 v[4:5], v[0:1], v[4:5] op_sel_hi:[0,1]
	s_waitcnt lgkmcnt(0)
	v_pk_add_f32 v[6:7], v[6:7], v[18:19]
	s_lshl_b32 s4, s1, 10
	v_pk_mul_f32 v[6:7], v[0:1], v[6:7] op_sel_hi:[0,1]
	s_or_b32 s0, s4, s0
	s_lshl_b32 s90, s1, 5
	v_add_u32_e32 v1, s0, v50
	v_lshl_add_u64 v[2:3], v[2:3], 0, s[90:91]
	s_waitcnt vmcnt(0)
	v_lshlrev_b32_e32 v24, 16, v190
	v_and_b32_e32 v25, 0xffff0000, v190
	v_lshlrev_b32_e32 v22, 16, v191
	v_and_b32_e32 v23, 0xffff0000, v191
	v_pk_mul_f32 v[4:5], v[4:5], v[24:25]
	v_pk_mul_f32 v[6:7], v[6:7], v[22:23]
	v_cvt_pk_bf16_f32 v4, v4, v5
	v_cvt_pk_bf16_f32 v5, v6, v7
	global_store_dwordx2 v[20:21], v[4:5], off
	ds_read2st64_b32 v[12:13], v1 offset1:1
	ds_read2st64_b32 v[14:15], v1 offset0:32 offset1:33
	ds_read2st64_b32 v[16:17], v1 offset0:64 offset1:65
	ds_read2st64_b32 v[18:19], v1 offset0:96 offset1:97
	ds_read2st64_b32 v[20:21], v1 offset0:2 offset1:3
	ds_read2st64_b32 v[10:11], v1 offset0:34 offset1:35
	ds_read2st64_b32 v[8:9], v1 offset0:66 offset1:67
	ds_read2st64_b32 v[4:5], v1 offset0:98 offset1:99
	s_waitcnt lgkmcnt(7)
	v_pk_add_f32 v[12:13], v[12:13], 0 op_sel_hi:[1,0]
	v_lshlrev_b32_e32 v22, 16, v192
	s_waitcnt lgkmcnt(6)
	v_pk_add_f32 v[12:13], v[12:13], v[14:15]
	s_waitcnt lgkmcnt(3)
	v_pk_add_f32 v[14:15], v[20:21], 0 op_sel_hi:[1,0]
	v_pk_add_f32 v[12:13], v[12:13], v[16:17]
	s_waitcnt lgkmcnt(2)
	v_pk_add_f32 v[10:11], v[14:15], v[10:11]
	v_pk_add_f32 v[12:13], v[12:13], v[18:19]
	s_waitcnt lgkmcnt(1)
	v_pk_add_f32 v[8:9], v[10:11], v[8:9]
	v_and_b32_e32 v23, 0xffff0000, v192
	s_waitcnt lgkmcnt(0)
	v_pk_add_f32 v[4:5], v[8:9], v[4:5]
	v_lshlrev_b32_e32 v6, 16, v193
	v_and_b32_e32 v7, 0xffff0000, v193
	v_pk_mul_f32 v[12:13], v[0:1], v[12:13] op_sel_hi:[0,1]
	v_pk_mul_f32 v[0:1], v[0:1], v[4:5] op_sel_hi:[0,1]
	v_pk_mul_f32 v[12:13], v[12:13], v[22:23]
	v_pk_mul_f32 v[0:1], v[0:1], v[6:7]
	v_cvt_pk_bf16_f32 v12, v12, v13
	v_cvt_pk_bf16_f32 v13, v0, v1
	global_store_dwordx2 v[2:3], v[12:13], off
	s_branch .LBB0_4832
.Latg_skip:
	s_waitcnt vmcnt(0)
	s_branch .LBB0_4832
